# differential loop role A: staging stores issued right after the overflow check, the 16 converts run while the LDS writes drain
# baseline (speedup 1.0000x reference)
; __device__ __forceinline__ s16x4 vtr(ldsp p) { return __builtin_bit_cast(s16x4, __builtin_amdgcn_ds_read_tr16_b64_v4i16((LAS v4i16_t*)p)); }
; template <bool DIFF>
; __device__ __forceinline__ void attn_unit(const AttnP& A, int b, int h, int qi, ldsp lds) {
;     ...
;             QK_BLOCK();
;             s16x4 vlo[8], vhi[8];
; #pragma unroll
;             for (int t = 0; t < 2; ++t)
; #pragma unroll
;                 for (int j = 0; j < 4; ++j) { vlo[t * 4 + j] = vtr(Vb + trb + (16 * j) * VP + t * 64); vhi[t * 4 + j] = vtr(Vb + trb + (16 * j + 8) * VP + t * 64); }
;             __builtin_amdgcn_sched_barrier(0);
;             MASK_BLOCK();
;             bool full = (kt == kt0);
;             float psa, psb;
;             if (!full) {
;                 EXPSUM_BLOCK();
;                 if (__any(psa + psb > 1.0e18f)) { full = true; QK_BLOCK();
;     ...
;             __builtin_amdgcn_s_setprio(1);
; #pragma unroll
;             for (int t = 0; t < 2; ++t)
; #pragma unroll
;                 for (int j = 0; j < 4; ++j) {
;                     const bf16x8 vf = (bf16x8){vlo[t * 4 + j][0], vlo[t * 4 + j][1], vlo[t * 4 + j][2], vlo[t * 4 + j][3], vhi[t * 4 + j][0], vhi[t * 4 + j][1], vhi[t * 4 + j][2], vhi[t * 4 + j][3]};
;                     o[t] = __builtin_amdgcn_mfma_f32_32x32x16_bf16(vf, pw[j], o[t], 0, 0, 0);
;                 }
;             if (DIFF) {
; #pragma unroll
;                 for (int t = 2; t < NTD; ++t)
; #pragma unroll
;                     for (int j = 0; j < 4; ++j) { vlo[(t - 2) * 4 + j] = vtr(Vb + trb + (16 * j) * VP + t * 64); vhi[(t - 2) * 4 + j] = vtr(Vb + trb + (16 * j + 8) * VP + t * 64); }
;                 __builtin_amdgcn_sched_barrier(0);
; #pragma unroll
;                 for (int t = 2; t < NTD; ++t)
; #pragma unroll
;                     for (int j = 0; j < 4; ++j) {
;                         const int i = (t - 2) * 4 + j;
;                         const bf16x8 vf = (bf16x8){vlo[i][0], vlo[i][1], vlo[i][2], vlo[i][3], vhi[i][0], vhi[i][1], vhi[i][2], vhi[i][3]};
;                         o[t] = __builtin_amdgcn_mfma_f32_32x32x16_bf16(vf, pw[j], o[t], 0, 0, 0);
;                     }
;             }
;             __builtin_amdgcn_s_setprio(0);
.Lda_s_even:
	ds_read_b64_tr_b16 v[148:149], v252 offset:17472
	ds_read_b64_tr_b16 v[150:151], v252 offset:20032
	ds_read_b64_tr_b16 v[152:153], v252 offset:17408
	ds_read_b64_tr_b16 v[154:155], v252 offset:19968
	ds_read_b64_tr_b16 v[156:157], v252 offset:22592
	ds_read_b64_tr_b16 v[158:159], v252 offset:25152
	ds_read_b64_tr_b16 v[160:161], v252 offset:22528
	ds_read_b64_tr_b16 v[162:163], v252 offset:25088
	ds_read_b64_tr_b16 v[164:165], v252 offset:27712
	ds_read_b64_tr_b16 v[166:167], v252 offset:30272
	ds_read_b64_tr_b16 v[168:169], v252 offset:27648
	ds_read_b64_tr_b16 v[170:171], v252 offset:30208
	ds_read_b64_tr_b16 v[172:173], v252 offset:32768
	ds_read_b64_tr_b16 v[174:175], v252 offset:35328
	ds_read_b64_tr_b16 v[176:177], v252 offset:32832
	ds_read_b64_tr_b16 v[178:179], v252 offset:35392
	s_waitcnt lgkmcnt(14)
	v_mfma_f32_32x32x16_bf16 v[34:49], v[148:151], v[98:101], v[34:49]
	ds_read_b64_tr_b16 v[90:91], v252 offset:17536
	ds_read_b64_tr_b16 v[92:93], v252 offset:20096
	s_waitcnt lgkmcnt(14)
	v_mfma_f32_32x32x16_bf16 v[50:65], v[152:155], v[98:101], v[50:65]
	ds_read_b64_tr_b16 v[94:95], v252 offset:17600
	ds_read_b64_tr_b16 v[96:97], v252 offset:20160
	s_waitcnt lgkmcnt(14)
	v_mfma_f32_32x32x16_bf16 v[34:49], v[156:159], v[102:105], v[34:49]
	ds_read_b64_tr_b16 v[106:107], v252 offset:22656
	ds_read_b64_tr_b16 v[108:109], v252 offset:25216
	s_waitcnt lgkmcnt(14)
	v_mfma_f32_32x32x16_bf16 v[50:65], v[160:163], v[102:105], v[50:65]
	ds_read_b64_tr_b16 v[110:111], v252 offset:22720
	ds_read_b64_tr_b16 v[112:113], v252 offset:25280
	s_waitcnt lgkmcnt(14)
	v_mfma_f32_32x32x16_bf16 v[34:49], v[164:167], v[82:85], v[34:49]
	ds_read_b64_tr_b16 v[240:241], v252 offset:27776
	ds_read_b64_tr_b16 v[242:243], v252 offset:30336
	s_waitcnt lgkmcnt(14)
	v_mfma_f32_32x32x16_bf16 v[50:65], v[168:171], v[82:85], v[50:65]
	ds_read_b64_tr_b16 v[148:149], v252 offset:27840
	ds_read_b64_tr_b16 v[150:151], v252 offset:30400
	s_waitcnt lgkmcnt(14)
	v_mfma_f32_32x32x16_bf16 v[50:65], v[172:175], v[86:89], v[50:65]
	ds_read_b64_tr_b16 v[152:153], v252 offset:32896
	ds_read_b64_tr_b16 v[154:155], v252 offset:35456
	s_waitcnt lgkmcnt(14)
	v_mfma_f32_32x32x16_bf16 v[34:49], v[176:179], v[86:89], v[34:49]
	ds_read_b64_tr_b16 v[156:157], v252 offset:32960
	ds_read_b64_tr_b16 v[158:159], v252 offset:35520
	s_waitcnt lgkmcnt(14)
	v_mfma_f32_32x32x16_bf16 v[18:33], v[90:93], v[98:101], v[18:33]
	ds_read_b128 v[160:163], v234
	s_waitcnt lgkmcnt(13)
	v_mfma_f32_32x32x16_bf16 v[2:17], v[94:97], v[98:101], v[2:17]
	ds_read_b128 v[164:167], v234 offset:8704
	s_waitcnt lgkmcnt(12)
	v_mfma_f32_32x32x16_bf16 v[18:33], v[106:109], v[102:105], v[18:33]
	ds_read_b128 v[168:171], v234 offset:32
	s_waitcnt lgkmcnt(11)
	v_mfma_f32_32x32x16_bf16 v[2:17], v[110:113], v[102:105], v[2:17]
	ds_read_b128 v[172:175], v234 offset:8736
	s_waitcnt lgkmcnt(10)
	v_mfma_f32_32x32x16_bf16 v[18:33], v[240:243], v[82:85], v[18:33]
	ds_read_b128 v[176:179], v234 offset:64
	s_waitcnt lgkmcnt(9)
	v_mfma_f32_32x32x16_bf16 v[2:17], v[148:151], v[82:85], v[2:17]
	ds_read_b128 v[240:243], v234 offset:8768
	s_waitcnt lgkmcnt(8)
	v_mfma_f32_32x32x16_bf16 v[18:33], v[152:155], v[86:89], v[18:33]
	ds_read_b128 v[148:151], v234 offset:96
	s_waitcnt lgkmcnt(7)
	v_mfma_f32_32x32x16_bf16 v[2:17], v[156:159], v[86:89], v[2:17]
	ds_read_b128 v[152:155], v234 offset:8800
	s_waitcnt lgkmcnt(7)
	v_mfma_f32_32x32x16_bf16 v[98:113], v[160:163], v[116:119], v[66:81]
	s_waitcnt lgkmcnt(6)
	v_mfma_f32_32x32x16_bf16 v[82:97], v[164:167], v[116:119], v[66:81]
	s_waitcnt lgkmcnt(5)
	v_mfma_f32_32x32x16_bf16 v[98:113], v[168:171], v[120:123], v[98:113]
	s_waitcnt lgkmcnt(4)
	v_mfma_f32_32x32x16_bf16 v[82:97], v[172:175], v[120:123], v[82:97]
	s_waitcnt lgkmcnt(3)
	v_mfma_f32_32x32x16_bf16 v[98:113], v[176:179], v[124:127], v[98:113]
	s_waitcnt lgkmcnt(2)
	v_mfma_f32_32x32x16_bf16 v[82:97], v[240:243], v[124:127], v[82:97]
	s_waitcnt lgkmcnt(1)
	v_mfma_f32_32x32x16_bf16 v[98:113], v[148:151], v[128:131], v[98:113]
	s_waitcnt lgkmcnt(0)
	v_mfma_f32_32x32x16_bf16 v[82:97], v[152:155], v[128:131], v[82:97]
	s_nop 7
	s_nop 3
	v_exp_f32_e32 v148, v98
	v_exp_f32_e32 v164, v82
	v_exp_f32_e32 v149, v99
	v_add_f32_e32 v237, 0, v148
	v_exp_f32_e32 v165, v83
	v_add_f32_e32 v238, 0, v164
	v_exp_f32_e32 v150, v100
	v_add_f32_e32 v237, v149, v237
	v_exp_f32_e32 v166, v84
	v_add_f32_e32 v238, v165, v238
	v_exp_f32_e32 v151, v101
	v_add_f32_e32 v237, v150, v237
	v_exp_f32_e32 v167, v85
	v_add_f32_e32 v238, v166, v238
	v_exp_f32_e32 v152, v102
	v_add_f32_e32 v237, v151, v237
	v_exp_f32_e32 v168, v86
	v_add_f32_e32 v238, v167, v238
	v_exp_f32_e32 v153, v103
	v_add_f32_e32 v237, v152, v237
	v_exp_f32_e32 v169, v87
	v_add_f32_e32 v238, v168, v238
	v_exp_f32_e32 v154, v104
	v_add_f32_e32 v237, v153, v237
	v_exp_f32_e32 v170, v88
	v_add_f32_e32 v238, v169, v238
	v_exp_f32_e32 v155, v105
	v_add_f32_e32 v237, v154, v237
	v_exp_f32_e32 v171, v89
	v_add_f32_e32 v238, v170, v238
	v_exp_f32_e32 v156, v106
	v_add_f32_e32 v237, v155, v237
	v_exp_f32_e32 v172, v90
	v_add_f32_e32 v238, v171, v238
	v_exp_f32_e32 v157, v107
	v_add_f32_e32 v237, v156, v237
	v_exp_f32_e32 v173, v91
	v_add_f32_e32 v238, v172, v238
	v_exp_f32_e32 v158, v108
	v_add_f32_e32 v237, v157, v237
	v_exp_f32_e32 v174, v92
	v_add_f32_e32 v238, v173, v238
	v_exp_f32_e32 v159, v109
	v_add_f32_e32 v237, v158, v237
	v_exp_f32_e32 v175, v93
	v_add_f32_e32 v238, v174, v238
	v_exp_f32_e32 v160, v110
	v_add_f32_e32 v237, v159, v237
	v_exp_f32_e32 v176, v94
	v_add_f32_e32 v238, v175, v238
	v_exp_f32_e32 v161, v111
	v_add_f32_e32 v237, v160, v237
	v_exp_f32_e32 v177, v95
	v_add_f32_e32 v238, v176, v238
	v_exp_f32_e32 v162, v112
	v_add_f32_e32 v237, v161, v237
	v_exp_f32_e32 v178, v96
	v_add_f32_e32 v238, v177, v238
	v_exp_f32_e32 v163, v113
	v_add_f32_e32 v237, v162, v237
	v_exp_f32_e32 v179, v97
	v_add_f32_e32 v238, v178, v238
	v_add_f32_e32 v237, v163, v237
	v_add_f32_e32 v238, v179, v238
	v_add_f32_e32 v204, v237, v238
	v_cmp_lt_f32_e32 vcc, s85, v204
	s_cbranch_vccnz .Lda_s_slow
; __device__ __forceinline__ unsigned cvtpk(float lo, float hi) { f32x2 v = {lo, hi}; bf16x2_t b = __builtin_convertvector(v, bf16x2_t); return __builtin_bit_cast(unsigned, b); }
; template <bool DIFF>
; __device__ __forceinline__ void attn_unit(const AttnP& A, int b, int h, int qi, ldsp lds) {
;     ...
;             l_run += psa + psb;
;     ...
;             bf16x8 pw[4];
; #pragma unroll
;             for (int j = 0; j < 4; ++j) {
;                 u32x4 pk;
;                 if (j < 2) { const int rb = 8 * (j & 1); pk.x = cvtpk(s0[rb], s0[rb + 1]); pk.y = cvtpk(s0[rb + 2], s0[rb + 3]); pk.z = cvtpk(s0[rb + 4], s0[rb + 5]); pk.w = cvtpk(s0[rb + 6], s0[rb + 7]); }
;                 else { const int rb = 8 * (j & 1); pk.x = cvtpk(s1[rb], s1[rb + 1]); pk.y = cvtpk(s1[rb + 2], s1[rb + 3]); pk.z = cvtpk(s1[rb + 4], s1[rb + 5]); pk.w = cvtpk(s1[rb + 6], s1[rb + 7]); }
;                 pw[j] = __builtin_bit_cast(bf16x8, pk);
;             }
;             __builtin_amdgcn_sched_barrier(0);
;             __builtin_amdgcn_s_setprio(1);
; #pragma unroll
;             for (int t = 0; t < 2; ++t)
; #pragma unroll
;                 for (int j = 0; j < 4; ++j) {
;                     const bf16x8 vf = (bf16x8){vlo[t * 4 + j][0], vlo[t * 4 + j][1], vlo[t * 4 + j][2], vlo[t * 4 + j][3], vhi[t * 4 + j][0], vhi[t * 4 + j][1], vhi[t * 4 + j][2], vhi[t * 4 + j][3]};
;                     o[t] = __builtin_amdgcn_mfma_f32_32x32x16_bf16(vf, pw[j], o[t], 0, 0, 0);
;                 }
;             if (DIFF) {
; #pragma unroll
;                 for (int t = 2; t < NTD; ++t)
; #pragma unroll
;                     for (int j = 0; j < 4; ++j) { vlo[(t - 2) * 4 + j] = vtr(Vb + trb + (16 * j) * VP + t * 64); vhi[(t - 2) * 4 + j] = vtr(Vb + trb + (16 * j + 8) * VP + t * 64); }
;                 __builtin_amdgcn_sched_barrier(0);
; #pragma unroll
;                 for (int t = 2; t < NTD; ++t)
; #pragma unroll
;                     for (int j = 0; j < 4; ++j) {
;                         const int i = (t - 2) * 4 + j;
;                         const bf16x8 vf = (bf16x8){vlo[i][0], vlo[i][1], vlo[i][2], vlo[i][3], vhi[i][0], vhi[i][1], vhi[i][2], vhi[i][3]};
;                         o[t] = __builtin_amdgcn_mfma_f32_32x32x16_bf16(vf, pw[j], o[t], 0, 0, 0);
;                     }
;             }
;             __builtin_amdgcn_s_setprio(0);
;         }
;         if (kt + 1 < nt) STORE_TILE((kt + 1) & 1);
	s_waitcnt vmcnt(0)
	ds_write_b128 v226, v[132:135] offset:38144
	ds_write_b128 v228, v[140:143] offset:38144
	ds_write_b128 v227, v[136:139] offset:17408
	ds_write_b128 v229, v[144:147] offset:17408
	global_load_dwordx4 v[136:139], v[196:197], off offset:2048
	global_load_dwordx4 v[144:147], v[198:199], off offset:2048
	v_lshl_add_u64 v[196:197], v[196:197], 0, s[26:27]
	v_lshl_add_u64 v[198:199], v[198:199], 0, s[26:27]
	global_load_dwordx4 v[132:135], v[196:197], off offset:1024
	global_load_dwordx4 v[140:143], v[198:199], off offset:1024
	v_cvt_pk_bf16_f32 v98, v148, v149
	v_cvt_pk_bf16_f32 v99, v150, v151
	v_cvt_pk_bf16_f32 v100, v152, v153
	v_cvt_pk_bf16_f32 v101, v154, v155
	v_cvt_pk_bf16_f32 v102, v156, v157
	v_cvt_pk_bf16_f32 v103, v158, v159
	v_cvt_pk_bf16_f32 v104, v160, v161
	v_cvt_pk_bf16_f32 v105, v162, v163
	v_cvt_pk_bf16_f32 v82, v164, v165
	v_cvt_pk_bf16_f32 v83, v166, v167
	v_cvt_pk_bf16_f32 v84, v168, v169
	v_cvt_pk_bf16_f32 v85, v170, v171
	v_cvt_pk_bf16_f32 v86, v172, v173
	v_cvt_pk_bf16_f32 v87, v174, v175
	v_cvt_pk_bf16_f32 v88, v176, v177
	v_cvt_pk_bf16_f32 v89, v178, v179
	v_add_f32_e32 v230, v204, v230
	s_waitcnt lgkmcnt(0)
	s_barrier
	s_add_i32 s75, s75, 1
	s_add_i32 s74, s74, 64
	s_cmp_gt_i32 s75, s23
	s_cbranch_scc1 .Lda_gen
.Lda_s_odd:
	ds_read_b64_tr_b16 v[148:149], v231 offset:17472
	ds_read_b64_tr_b16 v[150:151], v231 offset:20032
	ds_read_b64_tr_b16 v[152:153], v231 offset:17408
	ds_read_b64_tr_b16 v[154:155], v231 offset:19968
	ds_read_b64_tr_b16 v[156:157], v231 offset:22592
	ds_read_b64_tr_b16 v[158:159], v231 offset:25152
	ds_read_b64_tr_b16 v[160:161], v231 offset:22528
	ds_read_b64_tr_b16 v[162:163], v231 offset:25088
	ds_read_b64_tr_b16 v[164:165], v231 offset:27712
	ds_read_b64_tr_b16 v[166:167], v231 offset:30272
	ds_read_b64_tr_b16 v[168:169], v231 offset:27648
	ds_read_b64_tr_b16 v[170:171], v231 offset:30208
	ds_read_b64_tr_b16 v[172:173], v231 offset:32768
	ds_read_b64_tr_b16 v[174:175], v231 offset:35328
	ds_read_b64_tr_b16 v[176:177], v231 offset:32832
	ds_read_b64_tr_b16 v[178:179], v231 offset:35392
	s_waitcnt lgkmcnt(14)
	v_mfma_f32_32x32x16_bf16 v[34:49], v[148:151], v[98:101], v[34:49]
	ds_read_b64_tr_b16 v[90:91], v231 offset:17536
	ds_read_b64_tr_b16 v[92:93], v231 offset:20096
	s_waitcnt lgkmcnt(14)
	v_mfma_f32_32x32x16_bf16 v[50:65], v[152:155], v[98:101], v[50:65]
	ds_read_b64_tr_b16 v[94:95], v231 offset:17600
	ds_read_b64_tr_b16 v[96:97], v231 offset:20160
	s_waitcnt lgkmcnt(14)
	v_mfma_f32_32x32x16_bf16 v[34:49], v[156:159], v[102:105], v[34:49]
	ds_read_b64_tr_b16 v[106:107], v231 offset:22656
	ds_read_b64_tr_b16 v[108:109], v231 offset:25216
	s_waitcnt lgkmcnt(14)
	v_mfma_f32_32x32x16_bf16 v[50:65], v[160:163], v[102:105], v[50:65]
	ds_read_b64_tr_b16 v[110:111], v231 offset:22720
	ds_read_b64_tr_b16 v[112:113], v231 offset:25280
	s_waitcnt lgkmcnt(14)
	v_mfma_f32_32x32x16_bf16 v[34:49], v[164:167], v[82:85], v[34:49]
	ds_read_b64_tr_b16 v[240:241], v231 offset:27776
	ds_read_b64_tr_b16 v[242:243], v231 offset:30336
	s_waitcnt lgkmcnt(14)
	v_mfma_f32_32x32x16_bf16 v[50:65], v[168:171], v[82:85], v[50:65]
	ds_read_b64_tr_b16 v[148:149], v231 offset:27840
	ds_read_b64_tr_b16 v[150:151], v231 offset:30400
	s_waitcnt lgkmcnt(14)
	v_mfma_f32_32x32x16_bf16 v[50:65], v[172:175], v[86:89], v[50:65]
	ds_read_b64_tr_b16 v[152:153], v231 offset:32896
	ds_read_b64_tr_b16 v[154:155], v231 offset:35456
	s_waitcnt lgkmcnt(14)
	v_mfma_f32_32x32x16_bf16 v[34:49], v[176:179], v[86:89], v[34:49]
	ds_read_b64_tr_b16 v[156:157], v231 offset:32960
	ds_read_b64_tr_b16 v[158:159], v231 offset:35520
	s_waitcnt lgkmcnt(14)
	v_mfma_f32_32x32x16_bf16 v[18:33], v[90:93], v[98:101], v[18:33]
	ds_read_b128 v[160:163], v234 offset:38144
	s_waitcnt lgkmcnt(13)
	v_mfma_f32_32x32x16_bf16 v[2:17], v[94:97], v[98:101], v[2:17]
	ds_read_b128 v[164:167], v234 offset:46848
	s_waitcnt lgkmcnt(12)
	v_mfma_f32_32x32x16_bf16 v[18:33], v[106:109], v[102:105], v[18:33]
	ds_read_b128 v[168:171], v234 offset:38176
	s_waitcnt lgkmcnt(11)
	v_mfma_f32_32x32x16_bf16 v[2:17], v[110:113], v[102:105], v[2:17]
	ds_read_b128 v[172:175], v234 offset:46880
	s_waitcnt lgkmcnt(10)
	v_mfma_f32_32x32x16_bf16 v[18:33], v[240:243], v[82:85], v[18:33]
	ds_read_b128 v[176:179], v234 offset:38208
	s_waitcnt lgkmcnt(9)
; __device__ __forceinline__ s16x4 vtr(ldsp p) { return __builtin_bit_cast(s16x4, __builtin_amdgcn_ds_read_tr16_b64_v4i16((LAS v4i16_t*)p)); }
; template <bool DIFF>
; __device__ __forceinline__ void attn_unit(const AttnP& A, int b, int h, int qi, ldsp lds) {
;     ...
;             QK_BLOCK();
;             s16x4 vlo[8], vhi[8];
; #pragma unroll
;             for (int t = 0; t < 2; ++t)
; #pragma unroll
;                 for (int j = 0; j < 4; ++j) { vlo[t * 4 + j] = vtr(Vb + trb + (16 * j) * VP + t * 64); vhi[t * 4 + j] = vtr(Vb + trb + (16 * j + 8) * VP + t * 64); }
;             __builtin_amdgcn_sched_barrier(0);
;             MASK_BLOCK();
;             bool full = (kt == kt0);
;             float psa, psb;
;             if (!full) {
;                 EXPSUM_BLOCK();
;                 if (__any(psa + psb > 1.0e18f)) { full = true; QK_BLOCK();
; #pragma unroll
;                     for (int t = 0; t < 2; ++t)
; #pragma unroll
;                         for (int j = 0; j < 4; ++j) { vlo[t * 4 + j] = vtr(Vb + trb + (16 * j) * VP + t * 64); vhi[t * 4 + j] = vtr(Vb + trb + (16 * j + 8) * VP + t * 64); }
;                     MASK_BLOCK(); }
;             }
;             if (full) {
;                 float ma = fmaxf(fmaxf(s0[0], s0[1]), s1[0]), mb = fmaxf(fmaxf(s0[2], s0[3]), s1[1]);
;                 ma = fmaxf(fmaxf(ma, s1[2]), s1[3]);
; #pragma unroll
;                 for (int r = 4; r < 16; r += 4) { ma = fmaxf(fmaxf(ma, s0[r]), s0[r + 1]); mb = fmaxf(fmaxf(mb, s0[r + 2]), s0[r + 3]); ma = fmaxf(fmaxf(ma, s1[r]), s1[r + 1]); mb = fmaxf(fmaxf(mb, s1[r + 2]), s1[r + 3]); }
;                 const float rm = swap32_max(fmaxf(ma, mb));
;                 const float dl = (kt == kt0) ? ((rm == -INFINITY) ? 0.f : rm) : fmaxf(rm, 0.f);
;                 mhat += dl;
; #pragma unroll
;                 for (int r = 0; r < 16; ++r) { s0[r] -= dl; s1[r] -= dl; negm[r] = -mhat; }
;                 const float f = (kt == kt0) ? 1.0f : __builtin_amdgcn_exp2f(-dl);
;                 l_run *= f;
; #pragma unroll
;                 for (int t = 0; t < NTD; ++t)
; #pragma unroll
;                     for (int r = 0; r < 16; ++r) o[t][r] *= f;
;                 EXPSUM_BLOCK();
;             }
;             l_run += psa + psb;
;     ...
;             bf16x8 pw[4];
; #pragma unroll
;             for (int j = 0; j < 4; ++j) {
;                 u32x4 pk;
	v_mfma_f32_32x32x16_bf16 v[2:17], v[148:151], v[82:85], v[2:17]
	ds_read_b128 v[240:243], v234 offset:46912
	s_waitcnt lgkmcnt(8)
	v_mfma_f32_32x32x16_bf16 v[18:33], v[152:155], v[86:89], v[18:33]
	ds_read_b128 v[148:151], v234 offset:38240
	s_waitcnt lgkmcnt(7)
	v_mfma_f32_32x32x16_bf16 v[2:17], v[156:159], v[86:89], v[2:17]
	ds_read_b128 v[152:155], v234 offset:46944
	s_waitcnt lgkmcnt(7)
	v_mfma_f32_32x32x16_bf16 v[98:113], v[160:163], v[116:119], v[66:81]
	s_waitcnt lgkmcnt(6)
	v_mfma_f32_32x32x16_bf16 v[82:97], v[164:167], v[116:119], v[66:81]
	s_waitcnt lgkmcnt(5)
	v_mfma_f32_32x32x16_bf16 v[98:113], v[168:171], v[120:123], v[98:113]
	s_waitcnt lgkmcnt(4)
	v_mfma_f32_32x32x16_bf16 v[82:97], v[172:175], v[120:123], v[82:97]
	s_waitcnt lgkmcnt(3)
	v_mfma_f32_32x32x16_bf16 v[98:113], v[176:179], v[124:127], v[98:113]
	s_waitcnt lgkmcnt(2)
	v_mfma_f32_32x32x16_bf16 v[82:97], v[240:243], v[124:127], v[82:97]
	s_waitcnt lgkmcnt(1)
	v_mfma_f32_32x32x16_bf16 v[98:113], v[148:151], v[128:131], v[98:113]
	s_waitcnt lgkmcnt(0)
	v_mfma_f32_32x32x16_bf16 v[82:97], v[152:155], v[128:131], v[82:97]
	s_nop 7
	s_nop 3
	v_exp_f32_e32 v148, v98
	v_exp_f32_e32 v164, v82
	v_exp_f32_e32 v149, v99
	v_add_f32_e32 v237, 0, v148
	v_exp_f32_e32 v165, v83
	v_add_f32_e32 v238, 0, v164
	v_exp_f32_e32 v150, v100
	v_add_f32_e32 v237, v149, v237
	v_exp_f32_e32 v166, v84
	v_add_f32_e32 v238, v165, v238
	v_exp_f32_e32 v151, v101
	v_add_f32_e32 v237, v150, v237
	v_exp_f32_e32 v167, v85
	v_add_f32_e32 v238, v166, v238
	v_exp_f32_e32 v152, v102
	v_add_f32_e32 v237, v151, v237
	v_exp_f32_e32 v168, v86
	v_add_f32_e32 v238, v167, v238
	v_exp_f32_e32 v153, v103
	v_add_f32_e32 v237, v152, v237
	v_exp_f32_e32 v169, v87
	v_add_f32_e32 v238, v168, v238
	v_exp_f32_e32 v154, v104
	v_add_f32_e32 v237, v153, v237
	v_exp_f32_e32 v170, v88
	v_add_f32_e32 v238, v169, v238
	v_exp_f32_e32 v155, v105
	v_add_f32_e32 v237, v154, v237
	v_exp_f32_e32 v171, v89
	v_add_f32_e32 v238, v170, v238
	v_exp_f32_e32 v156, v106
	v_add_f32_e32 v237, v155, v237
	v_exp_f32_e32 v172, v90
	v_add_f32_e32 v238, v171, v238
	v_exp_f32_e32 v157, v107
	v_add_f32_e32 v237, v156, v237
	v_exp_f32_e32 v173, v91
	v_add_f32_e32 v238, v172, v238
	v_exp_f32_e32 v158, v108
	v_add_f32_e32 v237, v157, v237
	v_exp_f32_e32 v174, v92
	v_add_f32_e32 v238, v173, v238
	v_exp_f32_e32 v159, v109
	v_add_f32_e32 v237, v158, v237
	v_exp_f32_e32 v175, v93
	v_add_f32_e32 v238, v174, v238
	v_exp_f32_e32 v160, v110
	v_add_f32_e32 v237, v159, v237
	v_exp_f32_e32 v176, v94
	v_add_f32_e32 v238, v175, v238
	v_exp_f32_e32 v161, v111
	v_add_f32_e32 v237, v160, v237
	v_exp_f32_e32 v177, v95
	v_add_f32_e32 v238, v176, v238
	v_exp_f32_e32 v162, v112
	v_add_f32_e32 v237, v161, v237
	v_exp_f32_e32 v178, v96
	v_add_f32_e32 v238, v177, v238
	v_exp_f32_e32 v163, v113
	v_add_f32_e32 v237, v162, v237
	v_exp_f32_e32 v179, v97
	v_add_f32_e32 v238, v178, v238
	v_add_f32_e32 v237, v163, v237
	v_add_f32_e32 v238, v179, v238
	v_add_f32_e32 v204, v237, v238
	v_cmp_lt_f32_e32 vcc, s85, v204
	s_cbranch_vccnz .Lda_s_slow
	s_waitcnt vmcnt(0)
	ds_write_b128 v226, v[132:135]
	ds_write_b128 v228, v[140:143]
	ds_write_b128 v227, v[136:139] offset:55552
	ds_write_b128 v229, v[144:147] offset:55552
	global_load_dwordx4 v[136:139], v[196:197], off offset:2048
	global_load_dwordx4 v[144:147], v[198:199], off offset:2048
	v_lshl_add_u64 v[196:197], v[196:197], 0, s[26:27]
	v_lshl_add_u64 v[198:199], v[198:199], 0, s[26:27]
	global_load_dwordx4 v[132:135], v[196:197], off offset:1024
	global_load_dwordx4 v[140:143], v[198:199], off offset:1024
	v_cvt_pk_bf16_f32 v98, v148, v149
	v_cvt_pk_bf16_f32 v99, v150, v151
	v_cvt_pk_bf16_f32 v100, v152, v153
	v_cvt_pk_bf16_f32 v101, v154, v155
	v_cvt_pk_bf16_f32 v102, v156, v157
	v_cvt_pk_bf16_f32 v103, v158, v159
	v_cvt_pk_bf16_f32 v104, v160, v161
	v_cvt_pk_bf16_f32 v105, v162, v163
	v_cvt_pk_bf16_f32 v82, v164, v165
	v_cvt_pk_bf16_f32 v83, v166, v167
	v_cvt_pk_bf16_f32 v84, v168, v169
	v_cvt_pk_bf16_f32 v85, v170, v171
	v_cvt_pk_bf16_f32 v86, v172, v173
	v_cvt_pk_bf16_f32 v87, v174, v175
	v_cvt_pk_bf16_f32 v88, v176, v177
	v_cvt_pk_bf16_f32 v89, v178, v179
	v_add_f32_e32 v230, v204, v230
	s_waitcnt lgkmcnt(0)
	s_barrier
	s_add_i32 s75, s75, 1
	s_add_i32 s74, s74, 64
	s_cmp_le_i32 s75, s23
	s_cbranch_scc1 .Lda_s_even
